# P8 latent K-quarter epilogue hand-written: the four gate vectors loaded once, 32 partial-plane stores issued back to back (was a load + full wait in front of every store)
# baseline (speedup 1.0000x reference)
.LBB0_1662:
	s_and_b64 vcc, exec, s[34:35]
	s_cbranch_vccz .LBB0_1669
	global_load_dwordx4 v[160:163], v[154:155], off
	global_load_dwordx4 v[164:167], v[154:155], off offset:64
	global_load_dwordx4 v[168:171], v[154:155], off offset:512
	global_load_dwordx4 v[172:175], v[154:155], off offset:576
	s_add_i32 s16, s91, -1
	s_lshl_b64 s[26:27], s[16:17], 24
	s_add_u32 s26, s85, s26
	s_addc_u32 s27, s46, s27
	v_add_u32_e32 v128, 0xffffe000, v158
	v_lshlrev_b32_e32 v128, 13, v128
	v_lshl_add_u32 v128, v156, 2, v128
	v_mov_b32_e32 v176, v128
	v_add_u32_e32 v177, 0x20000, v128
	v_add_u32_e32 v178, 0x40000, v128
	v_add_u32_e32 v179, 0x60000, v128
	v_add_u32_e32 v180, 0x100000, v128
	v_add_u32_e32 v181, 0x120000, v128
	v_add_u32_e32 v182, 0x140000, v128
	v_add_u32_e32 v183, 0x160000, v128
	s_waitcnt vmcnt(0)
	v_pk_mul_f32 v[124:125], v[124:125], v[160:161]
	v_pk_mul_f32 v[126:127], v[126:127], v[162:163]
	global_store_dwordx4 v176, v[124:127], s[26:27] offset:0
	v_pk_mul_f32 v[120:121], v[120:121], v[164:165]
	v_pk_mul_f32 v[122:123], v[122:123], v[166:167]
	global_store_dwordx4 v176, v[120:123], s[26:27] offset:64
	v_pk_mul_f32 v[116:117], v[116:117], v[168:169]
	v_pk_mul_f32 v[118:119], v[118:119], v[170:171]
	global_store_dwordx4 v176, v[116:119], s[26:27] offset:512
	v_pk_mul_f32 v[108:109], v[108:109], v[172:173]
	v_pk_mul_f32 v[110:111], v[110:111], v[174:175]
	global_store_dwordx4 v176, v[108:111], s[26:27] offset:576
	v_pk_mul_f32 v[112:113], v[112:113], v[160:161]
	v_pk_mul_f32 v[114:115], v[114:115], v[162:163]
	global_store_dwordx4 v177, v[112:115], s[26:27] offset:0
	v_pk_mul_f32 v[104:105], v[104:105], v[164:165]
	v_pk_mul_f32 v[106:107], v[106:107], v[166:167]
	global_store_dwordx4 v177, v[104:107], s[26:27] offset:64
	v_pk_mul_f32 v[100:101], v[100:101], v[168:169]
	v_pk_mul_f32 v[102:103], v[102:103], v[170:171]
	global_store_dwordx4 v177, v[100:103], s[26:27] offset:512
	v_pk_mul_f32 v[92:93], v[92:93], v[172:173]
	v_pk_mul_f32 v[94:95], v[94:95], v[174:175]
	global_store_dwordx4 v177, v[92:95], s[26:27] offset:576
	v_pk_mul_f32 v[96:97], v[96:97], v[160:161]
	v_pk_mul_f32 v[98:99], v[98:99], v[162:163]
	global_store_dwordx4 v178, v[96:99], s[26:27] offset:0
	v_pk_mul_f32 v[88:89], v[88:89], v[164:165]
	v_pk_mul_f32 v[90:91], v[90:91], v[166:167]
	global_store_dwordx4 v178, v[88:91], s[26:27] offset:64
	v_pk_mul_f32 v[84:85], v[84:85], v[168:169]
	v_pk_mul_f32 v[86:87], v[86:87], v[170:171]
	global_store_dwordx4 v178, v[84:87], s[26:27] offset:512
	v_pk_mul_f32 v[76:77], v[76:77], v[172:173]
	v_pk_mul_f32 v[78:79], v[78:79], v[174:175]
	global_store_dwordx4 v178, v[76:79], s[26:27] offset:576
	v_pk_mul_f32 v[80:81], v[80:81], v[160:161]
	v_pk_mul_f32 v[82:83], v[82:83], v[162:163]
	global_store_dwordx4 v179, v[80:83], s[26:27] offset:0
	v_pk_mul_f32 v[72:73], v[72:73], v[164:165]
	v_pk_mul_f32 v[74:75], v[74:75], v[166:167]
	global_store_dwordx4 v179, v[72:75], s[26:27] offset:64
	v_pk_mul_f32 v[68:69], v[68:69], v[168:169]
	v_pk_mul_f32 v[70:71], v[70:71], v[170:171]
	global_store_dwordx4 v179, v[68:71], s[26:27] offset:512
	v_pk_mul_f32 v[64:65], v[64:65], v[172:173]
	v_pk_mul_f32 v[66:67], v[66:67], v[174:175]
	global_store_dwordx4 v179, v[64:67], s[26:27] offset:576
	v_pk_mul_f32 v[60:61], v[60:61], v[160:161]
	v_pk_mul_f32 v[62:63], v[62:63], v[162:163]
	global_store_dwordx4 v180, v[60:63], s[26:27] offset:0
	v_pk_mul_f32 v[56:57], v[56:57], v[164:165]
	v_pk_mul_f32 v[58:59], v[58:59], v[166:167]
	global_store_dwordx4 v180, v[56:59], s[26:27] offset:64
	v_pk_mul_f32 v[52:53], v[52:53], v[168:169]
	v_pk_mul_f32 v[54:55], v[54:55], v[170:171]
	global_store_dwordx4 v180, v[52:55], s[26:27] offset:512
	v_pk_mul_f32 v[44:45], v[44:45], v[172:173]
	v_pk_mul_f32 v[46:47], v[46:47], v[174:175]
	global_store_dwordx4 v180, v[44:47], s[26:27] offset:576
	v_pk_mul_f32 v[48:49], v[48:49], v[160:161]
	v_pk_mul_f32 v[50:51], v[50:51], v[162:163]
	global_store_dwordx4 v181, v[48:51], s[26:27] offset:0
	v_pk_mul_f32 v[40:41], v[40:41], v[164:165]
	v_pk_mul_f32 v[42:43], v[42:43], v[166:167]
	global_store_dwordx4 v181, v[40:43], s[26:27] offset:64
	v_pk_mul_f32 v[36:37], v[36:37], v[168:169]
	v_pk_mul_f32 v[38:39], v[38:39], v[170:171]
	global_store_dwordx4 v181, v[36:39], s[26:27] offset:512
	v_pk_mul_f32 v[28:29], v[28:29], v[172:173]
	v_pk_mul_f32 v[30:31], v[30:31], v[174:175]
	global_store_dwordx4 v181, v[28:31], s[26:27] offset:576
	v_pk_mul_f32 v[32:33], v[32:33], v[160:161]
	v_pk_mul_f32 v[34:35], v[34:35], v[162:163]
	global_store_dwordx4 v182, v[32:35], s[26:27] offset:0
	v_pk_mul_f32 v[24:25], v[24:25], v[164:165]
	v_pk_mul_f32 v[26:27], v[26:27], v[166:167]
	global_store_dwordx4 v182, v[24:27], s[26:27] offset:64
	v_pk_mul_f32 v[20:21], v[20:21], v[168:169]
	v_pk_mul_f32 v[22:23], v[22:23], v[170:171]
	global_store_dwordx4 v182, v[20:23], s[26:27] offset:512
	v_pk_mul_f32 v[12:13], v[12:13], v[172:173]
	v_pk_mul_f32 v[14:15], v[14:15], v[174:175]
	global_store_dwordx4 v182, v[12:15], s[26:27] offset:576
	v_pk_mul_f32 v[16:17], v[16:17], v[160:161]
	v_pk_mul_f32 v[18:19], v[18:19], v[162:163]
	global_store_dwordx4 v183, v[16:19], s[26:27] offset:0
	v_pk_mul_f32 v[8:9], v[8:9], v[164:165]
	v_pk_mul_f32 v[10:11], v[10:11], v[166:167]
	global_store_dwordx4 v183, v[8:11], s[26:27] offset:64
	v_pk_mul_f32 v[4:5], v[4:5], v[168:169]
	v_pk_mul_f32 v[6:7], v[6:7], v[170:171]
	global_store_dwordx4 v183, v[4:7], s[26:27] offset:512
	v_pk_mul_f32 v[0:1], v[0:1], v[172:173]
	v_pk_mul_f32 v[2:3], v[2:3], v[174:175]
	global_store_dwordx4 v183, v[0:3], s[26:27] offset:576
	s_and_b64 vcc, exec, s[72:73]
	s_mov_b64 s[8:9], -1
	s_cbranch_vccnz .LBB0_1615
	s_branch .LBB0_1670
